# lad + S5-table D-term load hoisted (1 round trip instead of 16) + dead zq re-reads removed in S5A prologue + P0 row split 12/20
# speedup vs baseline: 1.0142x; 1.0035x over previous
.LBB0_32:
	s_or_b64 exec, exec, s[4:5]
	s_movk_i32 s4, 0x100
	v_cmp_gt_u32_e32 vcc, s4, v0
	s_waitcnt lgkmcnt(0)
	s_barrier
	s_and_saveexec_b64 s[12:13], vcc
	s_cbranch_execz .LBB0_66
	v_lshlrev_b32_e32 v18, 6, v0
	v_add_u32_e32 v20, 0, v18
	ds_read_b32 v21, v20 offset:49152
	v_lshl_or_b32 v18, s10, 4, v56
	v_or_b32_e32 v22, v57, v56
	v_ashrrev_i32_e32 v19, 31, v18
	s_add_i32 s14, 0, 0x230d0
	v_mov_b32_e32 v100, s14
	ds_read_b64 v[100:101], v100
	s_waitcnt lgkmcnt(0)
	v_readfirstlane_b32 s14, v100
	v_readfirstlane_b32 s15, v101
	s_nop 0
	v_mov_b32_e32 v100, s14
	v_mov_b32_e32 v101, s15
	v_lshl_add_u64 v[100:101], v[18:19], 2, v[100:101]
	global_load_dword v100, v[100:101], off
	v_cmp_eq_u32_e32 vcc, 0, v22
	s_waitcnt lgkmcnt(0)
	v_add_f32_e32 v14, v14, v21
	s_waitcnt vmcnt(0)
	s_and_saveexec_b64 s[4:5], vcc
	s_cbranch_execz .LBB0_35
	v_add_f32_e32 v14, v14, v100
.LBB0_35:
	s_or_b64 exec, exec, s[4:5]
	ds_read_b32 v21, v20 offset:49156
	v_cmp_eq_u32_e32 vcc, 0, v42
	v_cmp_eq_u32_e64 s[4:5], 1, v56
	ds_write_b32 v20, v14 offset:49152
	s_and_b64 s[14:15], s[4:5], vcc
	s_waitcnt lgkmcnt(1)
	v_add_f32_e32 v14, v15, v21
	s_and_saveexec_b64 s[4:5], s[14:15]
	s_cbranch_execz .LBB0_37
	v_add_f32_e32 v14, v14, v100
.LBB0_37:
	s_or_b64 exec, exec, s[4:5]
	ds_read_b32 v15, v20 offset:49160
	v_cmp_eq_u32_e64 s[4:5], 2, v56
	ds_write_b32 v20, v14 offset:49156
	s_and_b64 s[14:15], s[4:5], vcc
	s_waitcnt lgkmcnt(1)
	v_add_f32_e32 v14, v16, v15
	s_and_saveexec_b64 s[4:5], s[14:15]
	s_cbranch_execz .LBB0_39
	v_add_f32_e32 v14, v14, v100
.LBB0_39:
	s_or_b64 exec, exec, s[4:5]
	ds_read_b32 v15, v20 offset:49164
	v_cmp_eq_u32_e64 s[4:5], 3, v56
	ds_write_b32 v20, v14 offset:49160
	s_and_b64 s[14:15], s[4:5], vcc
	s_waitcnt lgkmcnt(1)
	v_add_f32_e32 v14, v17, v15
	s_and_saveexec_b64 s[4:5], s[14:15]
	s_cbranch_execz .LBB0_41
	v_add_f32_e32 v14, v14, v100
.LBB0_41:
	s_or_b64 exec, exec, s[4:5]
	ds_read_b32 v15, v20 offset:49168
	v_cmp_eq_u32_e64 s[4:5], 4, v56
	s_and_b64 s[14:15], s[4:5], vcc
	ds_write_b32 v20, v14 offset:49164
	s_waitcnt lgkmcnt(1)
	v_add_f32_e32 v10, v10, v15
	s_and_saveexec_b64 s[4:5], s[14:15]
	s_cbranch_execz .LBB0_43
	v_add_f32_e32 v10, v10, v100
.LBB0_43:
	s_or_b64 exec, exec, s[4:5]
	ds_read_b32 v14, v20 offset:49172
	v_cmp_eq_u32_e64 s[4:5], 5, v56
	ds_write_b32 v20, v10 offset:49168
	s_and_b64 s[14:15], s[4:5], vcc
	s_waitcnt lgkmcnt(1)
	v_add_f32_e32 v10, v11, v14
	s_and_saveexec_b64 s[4:5], s[14:15]
	s_cbranch_execz .LBB0_45
	v_add_f32_e32 v10, v10, v100
.LBB0_45:
	s_or_b64 exec, exec, s[4:5]
	ds_read_b32 v11, v20 offset:49176
	v_cmp_eq_u32_e64 s[4:5], 6, v56
	ds_write_b32 v20, v10 offset:49172
	s_and_b64 s[14:15], s[4:5], vcc
	s_waitcnt lgkmcnt(1)
	v_add_f32_e32 v10, v12, v11
	s_and_saveexec_b64 s[4:5], s[14:15]
	s_cbranch_execz .LBB0_47
	v_add_f32_e32 v10, v10, v100
.LBB0_47:
	s_or_b64 exec, exec, s[4:5]
	ds_read_b32 v11, v20 offset:49180
	v_cmp_eq_u32_e64 s[4:5], 7, v56
	ds_write_b32 v20, v10 offset:49176
	s_and_b64 s[14:15], s[4:5], vcc
	s_waitcnt lgkmcnt(1)
	v_add_f32_e32 v10, v13, v11
	s_and_saveexec_b64 s[4:5], s[14:15]
	s_cbranch_execz .LBB0_49
	v_add_f32_e32 v10, v10, v100
.LBB0_49:
	s_or_b64 exec, exec, s[4:5]
	ds_read_b32 v11, v20 offset:49184
	v_cmp_eq_u32_e64 s[4:5], 8, v56
	s_and_b64 s[14:15], s[4:5], vcc
	ds_write_b32 v20, v10 offset:49180
	s_waitcnt lgkmcnt(1)
	v_add_f32_e32 v6, v6, v11
	s_and_saveexec_b64 s[4:5], s[14:15]
	s_cbranch_execz .LBB0_51
	v_add_f32_e32 v6, v6, v100
.LBB0_51:
	s_or_b64 exec, exec, s[4:5]
	ds_read_b32 v10, v20 offset:49188
	v_cmp_eq_u32_e64 s[4:5], 9, v56
	ds_write_b32 v20, v6 offset:49184
	s_and_b64 s[14:15], s[4:5], vcc
	s_waitcnt lgkmcnt(1)
	v_add_f32_e32 v6, v7, v10
	s_and_saveexec_b64 s[4:5], s[14:15]
	s_cbranch_execz .LBB0_53
	v_add_f32_e32 v6, v6, v100
.LBB0_53:
	s_or_b64 exec, exec, s[4:5]
	ds_read_b32 v7, v20 offset:49192
	v_cmp_eq_u32_e64 s[4:5], 10, v56
	ds_write_b32 v20, v6 offset:49188
	s_and_b64 s[14:15], s[4:5], vcc
	s_waitcnt lgkmcnt(1)
	v_add_f32_e32 v6, v8, v7
	s_and_saveexec_b64 s[4:5], s[14:15]
	s_cbranch_execz .LBB0_55
	v_add_f32_e32 v6, v6, v100
.LBB0_55:
	s_or_b64 exec, exec, s[4:5]
	ds_read_b32 v7, v20 offset:49196
	v_cmp_eq_u32_e64 s[4:5], 11, v56
	ds_write_b32 v20, v6 offset:49192
	s_and_b64 s[14:15], s[4:5], vcc
	s_waitcnt lgkmcnt(1)
	v_add_f32_e32 v6, v9, v7
	s_and_saveexec_b64 s[4:5], s[14:15]
	s_cbranch_execz .LBB0_57
	v_add_f32_e32 v6, v6, v100
.LBB0_57:
	s_or_b64 exec, exec, s[4:5]
	ds_read_b32 v7, v20 offset:49200
	v_cmp_eq_u32_e64 s[4:5], 12, v56
	s_and_b64 s[14:15], s[4:5], vcc
	ds_write_b32 v20, v6 offset:49196
	s_waitcnt lgkmcnt(1)
	v_add_f32_e32 v2, v2, v7
	s_and_saveexec_b64 s[4:5], s[14:15]
	s_cbranch_execz .LBB0_59
	v_add_f32_e32 v2, v2, v100
.LBB0_59:
	s_or_b64 exec, exec, s[4:5]
	ds_read_b32 v6, v20 offset:49204
	v_cmp_eq_u32_e64 s[4:5], 13, v56
	ds_write_b32 v20, v2 offset:49200
	s_and_b64 s[14:15], s[4:5], vcc
	s_waitcnt lgkmcnt(1)
	v_add_f32_e32 v2, v3, v6
	s_and_saveexec_b64 s[4:5], s[14:15]
	s_cbranch_execz .LBB0_61
	v_add_f32_e32 v2, v2, v100
.LBB0_61:
	s_or_b64 exec, exec, s[4:5]
	ds_read_b32 v3, v20 offset:49208
	v_cmp_eq_u32_e64 s[4:5], 14, v56
	ds_write_b32 v20, v2 offset:49204
	s_and_b64 s[14:15], s[4:5], vcc
	s_waitcnt lgkmcnt(1)
	v_add_f32_e32 v2, v4, v3
	s_and_saveexec_b64 s[4:5], s[14:15]
	s_cbranch_execz .LBB0_63
	v_add_f32_e32 v2, v2, v100
.LBB0_63:
	s_or_b64 exec, exec, s[4:5]
	ds_read_b32 v3, v20 offset:49212
	v_cmp_eq_u32_e64 s[4:5], 15, v56
	ds_write_b32 v20, v2 offset:49208
	s_and_b64 s[14:15], s[4:5], vcc
	s_waitcnt lgkmcnt(1)
	v_add_f32_e32 v2, v5, v3
	s_and_saveexec_b64 s[4:5], s[14:15]
	s_cbranch_execz .LBB0_65
	v_add_f32_e32 v2, v2, v100

.LBB0_152:
.LBB0_153:
	s_and_b64 s[8:9], s[8:9], exec
	s_cselect_b32 s14, 12, 20
.LBB0_154:
	s_andn2_b64 vcc, exec, s[10:11]
	s_mov_b32 s8, s39
	s_cbranch_vccnz .LBB0_160
	s_and_b64 vcc, exec, s[6:7]
	s_cbranch_vccz .LBB0_157
	s_add_i32 s6, s63, s3
	s_add_i32 s8, s6, 0x2c00
	s_cbranch_execz .LBB0_158
	s_branch .LBB0_159

.LBB0_341:
	s_cmp_lt_i32 s44, 3
	s_cselect_b64 s[4:5], -1, 0
	s_cmp_gt_i32 s45, 2
	s_cselect_b64 s[6:7], -1, 0
	s_and_b64 s[4:5], s[4:5], s[6:7]
	s_andn2_b64 vcc, exec, s[4:5]
	s_cbranch_vccnz .LBB0_578
	s_add_u32 s39, s42, 0x6800000
	s_addc_u32 s41, s43, 0
	s_waitcnt lgkmcnt(0)
	v_mov_b32_e32 v84, v0
	s_cmpk_lt_i32 s40, 0x100
	s_movk_i32 s8, 0x100
	v_readfirstlane_b32 s12, v84
	s_cselect_b64 s[10:11], -1, 0
	s_cmpk_gt_i32 s40, 0xff
	s_cbranch_scc1 .LBB0_458
	v_lshlrev_b32_e32 v2, 4, v84
	v_add_u32_e32 v3, 0x2000, v2
	v_ashrrev_i32_e32 v4, 31, v3
	v_lshrrev_b32_e32 v4, 22, v4
	v_add_u32_e32 v4, v3, v4
	v_ashrrev_i32_e32 v83, 10, v4
	v_lshlrev_b32_e32 v4, 5, v83
	v_and_b32_e32 v82, 32, v4
	v_mul_i32_i24_e32 v4, 0x400, v83
	v_sub_u32_e32 v3, v3, v4
	v_lshrrev_b32_e32 v4, 4, v3
	v_bitop3_b32 v3, v4, v3, 32 bitop3:0x6c
	v_ashrrev_i32_e32 v4, 31, v3
	v_lshrrev_b32_e32 v4, 26, v4
	v_add_u32_e32 v4, v3, v4
	v_ashrrev_i32_e32 v85, 6, v4
	v_and_b32_e32 v4, 0xc0, v4
	v_sub_u32_e32 v3, v3, v4
	v_mov_b32_e32 v4, 1
	v_lshlrev_b32_e32 v5, 3, v83
	v_ashrrev_i16_sdwa v3, v4, sext(v3) dst_sel:DWORD dst_unused:UNUSED_PAD src0_sel:DWORD src1_sel:BYTE_0
	v_and_b32_e32 v5, -16, v5
	v_bfe_i32 v86, v3, 0, 16
	v_add_u32_e32 v5, v85, v5
	s_movk_i32 s15, 0x180
	v_add_u32_e32 v3, v82, v86
	s_waitcnt vmcnt(0)
	v_lshlrev_b32_e32 v6, 9, v5
	v_mul_lo_u32 v5, v5, s15
	v_lshl_add_u32 v66, v3, 1, v6
	v_add_lshl_u32 v68, v3, v5, 1
	v_ashrrev_i32_e32 v3, 31, v84
	v_lshrrev_b32_e32 v3, 26, v3
	v_add_u32_e32 v3, v84, v3
	v_ashrrev_i32_e32 v88, 6, v3
	v_lshlrev_b32_e32 v3, 5, v88
	v_and_b32_e32 v87, 32, v3
	v_bfe_i32 v3, v84, 27, 1
	v_lshrrev_b32_e32 v3, 22, v3
	v_add_u32_e32 v3, v2, v3
	s_add_u32 s28, s42, 0x1800000
	v_and_b32_e32 v3, 0xfffffc00, v3
	s_addc_u32 s29, s43, 0
	v_sub_u32_e32 v2, v2, v3
	s_lshl_b32 s4, s40, 2
	v_lshrrev_b32_e32 v3, 4, v2
	s_and_b32 s4, s4, 28
	s_bfe_u32 s78, s40, 0x20003
	v_bitop3_b32 v2, v3, v2, 32 bitop3:0x6c
	s_or_b32 s79, s4, s78
	v_ashrrev_i32_e32 v3, 31, v2
	s_ashr_i32 s4, s40, 5
	s_lshl_b32 s5, s79, 3
	s_ashr_i32 s6, s12, 6
	v_lshrrev_b32_e32 v3, 26, v3
	s_add_i32 s4, s5, s4
	s_ashr_i32 s9, s12, 8
	s_lshl_b32 s14, s6, 10
	v_add_u32_e32 v3, v2, v3
	s_mul_hi_i32 s5, s4, 0x30000
	s_mul_i32 s4, s4, 0x30000
	v_ashrrev_i32_e32 v90, 6, v3
	v_and_b32_e32 v3, 0xc0, v3
	s_add_u32 s20, s39, s4
	v_sub_u32_e32 v2, v2, v3
	v_lshlrev_b32_e32 v3, 3, v88
	s_addc_u32 s21, s41, s5
	s_lshl_b32 s4, s79, 17
	v_ashrrev_i16_sdwa v2, v4, sext(v2) dst_sel:DWORD dst_unused:UNUSED_PAD src0_sel:DWORD src1_sel:BYTE_0
	v_and_b32_e32 v3, -16, v3
	s_add_u32 s22, s28, s4
	v_bfe_i32 v89, v2, 0, 16
	v_add_u32_e32 v3, v90, v3
	s_addc_u32 s23, s29, 0
	s_add_i32 s30, 0, 0x23040
	v_add_u32_e32 v2, v87, v89
	v_lshlrev_b32_e32 v4, 9, v3
	v_mul_lo_u32 v3, v3, s15
	v_mov_b32_e32 v67, s30
	s_add_i32 s31, s14, 0
	v_lshl_add_u32 v70, v2, 1, v4
	v_add_lshl_u32 v72, v2, v3, 1
	ds_read_b128 v[62:65], v67
	ds_read_b128 v[58:61], v67
	ds_read_b128 v[54:57], v67
	ds_read_b128 v[50:53], v67
	ds_read_b128 v[46:49], v67
	ds_read_b128 v[42:45], v67
	ds_read_b128 v[34:37], v67
	ds_read_b128 v[26:29], v67
	ds_read_b128 v[38:41], v67
	ds_read_b128 v[30:33], v67
	ds_read_b128 v[22:25], v67
	ds_read_b128 v[18:21], v67
	ds_read_b128 v[14:17], v67
	ds_read_b128 v[10:13], v67
	ds_read_b128 v[6:9], v67
	s_add_i32 m0, s31, 0x10000
	ds_read_b128 v[2:5], v67
	ds_read_b128 v[74:77], v67
	global_load_lds_dwordx4 v70, s[22:23]
	s_add_i32 m0, s31, 0x12000
	s_add_u32 s4, s22, 0x10000
	s_addc_u32 s5, s23, 0
	s_add_i32 s34, s31, 0x14000
	global_load_lds_dwordx4 v66, s[22:23]
	s_mov_b32 m0, s34
	s_add_i32 s35, s31, 0x16000
	global_load_lds_dwordx4 v70, s[4:5]
	s_mov_b32 m0, s35
	s_add_i32 s52, s31, 0x2000
	global_load_lds_dwordx4 v66, s[4:5]
	s_mov_b32 m0, s31
	s_add_u32 s4, s20, 0x18000
	global_load_lds_dwordx4 v72, s[20:21]
	s_mov_b32 m0, s52
	s_addc_u32 s5, s21, 0
	s_add_i32 s53, s31, 0x4000
	global_load_lds_dwordx4 v68, s[20:21]
	s_mov_b32 m0, s53
	s_add_i32 s54, s31, 0x6000
	global_load_lds_dwordx4 v72, s[4:5]
	s_mov_b32 m0, s54
	v_mov_b32_e32 v71, 0
	global_load_lds_dwordx4 v68, s[4:5]
	v_mov_b32_e32 v67, v71
	v_mov_b32_e32 v73, v71
	v_mov_b32_e32 v69, v71
	s_cmp_eq_u32 s9, 1
	s_mov_b32 s55, 0
	v_lshl_add_u64 v[80:81], s[22:23], 0, v[70:71]
	v_lshl_add_u64 v[78:79], s[22:23], 0, v[66:67]
	s_waitcnt lgkmcnt(0)
	v_lshl_add_u64 v[74:75], s[20:21], 0, v[72:73]
	s_cselect_b64 s[4:5], -1, 0
	s_cmp_lg_u32 s9, 1
	v_lshl_add_u64 v[76:77], s[20:21], 0, v[68:69]
	s_cbranch_scc1 .LBB0_345
	s_barrier
